# attention: the causal mask code runs only on each wave's own diagonal key tile (earlier band tiles are fully visible to that wave)
# speedup vs baseline: 1.0079x; 1.0079x over previous
.LBB0_775:
	s_or_b64 exec, exec, s[4:5]
	s_and_b32 s60, s40, 0xff
	s_lshr_b32 s61, s60, 3
	s_sub_u32 s61, 15, s61
	s_and_b32 s64, s60, 7
	s_lshl_b32 s65, s44, 1
	s_lshl_b32 s45, s61, 2
	s_add_u32 s45, s45, 4
	s_sub_u32 s72, s45, 4
	v_lshrrev_b32_e32 v0, 6, v236
	s_nop 0
	v_readfirstlane_b32 s47, v0
	s_lshr_b32 s60, s47, 1
	s_add_u32 s78, s45, s60
	s_sub_u32 s78, s78, 3
	s_sub_u32 s79, s78, 1
	s_lshl_b32 s66, s64, 22
	s_lshr_b32 s67, s65, 1
	s_lshl_b32 s67, s67, 7
	s_add_u32 s48, s82, 0x9000000
	s_addc_u32 s49, s83, 0
	s_add_u32 s48, s48, s66
	s_addc_u32 s49, s49, 0
	s_add_u32 s48, s48, s67
	s_addc_u32 s49, s49, 0
	s_lshr_b32 s63, s65, 2
	s_lshl_b32 s63, s63, 8
	s_add_u32 s50, s82, 0xb000000
	s_addc_u32 s51, s83, 0
	s_add_u32 s50, s50, s66
	s_addc_u32 s51, s51, 0
	s_add_u32 s50, s50, s63
	s_addc_u32 s51, s51, 0
	s_lshl_b32 s63, s61, 8
	s_lshl_b32 s60, s47, 5
	s_add_u32 s63, s63, s60
	s_lshl_b32 s60, s63, 10
	s_add_u32 s54, s82, 0x7000000
	s_addc_u32 s55, s83, 0
	s_add_u32 s54, s54, s66
	s_addc_u32 s55, s55, 0
	s_add_u32 s54, s54, s60
	s_addc_u32 s55, s55, 0
	s_add_u32 s54, s54, s67
	s_addc_u32 s55, s55, 0
	s_lshl_b32 s60, s64, 12
	s_add_u32 s60, s60, s63
	s_lshl_b32 s60, s60, 11
	s_and_b32 s67, s65, 14
	s_lshl_b32 s67, s67, 7
	s_add_u32 s52, s82, 0x16000000
	s_addc_u32 s53, s83, 0
	s_add_u32 s52, s52, s60
	s_addc_u32 s53, s53, 0
	s_add_u32 s52, s52, s67
	s_addc_u32 s53, s53, 0
	v_and_b32_e32 v237, 63, v236
	v_lshrrev_b32_e32 v252, 5, v237
	v_and_b32_e32 v0, 31, v237
	s_lshl_b32 s60, s47, 4
	v_lshl_add_u32 v238, v237, 10, s60
	s_and_b32 s60, s47, 3
	s_lshl_b32 s60, s60, 14
	s_lshr_b32 s61, s47, 2
	s_lshl_b32 s61, s61, 6
	s_add_u32 s60, s60, s61
	v_lshrrev_b32_e32 v1, 2, v237
	v_lshlrev_b32_e32 v1, 10, v1
	v_and_b32_e32 v2, 3, v237
	v_lshl_or_b32 v1, v2, 4, v1
	v_add_u32_e32 v239, s60, v1
	v_lshlrev_b32_e32 v244, 10, v252
	v_lshl_or_b32 v244, v0, 4, v244
	v_bfe_u32 v1, v237, 4, 1
	v_lshlrev_b32_e32 v1, 5, v1
	v_lshl_or_b32 v1, v2, 3, v1
	v_bfe_u32 v2, v237, 2, 2
	v_lshl_or_b32 v2, v252, 2, v2
	v_lshl_or_b32 v1, v2, 6, v1
	v_add_u32_e32 v245, 24576, v1
	s_lshl_b32 s60, s47, 5
	v_add_u32_e32 v246, s60, v0
	s_lshl_b32 s60, s47, 8
	s_add_u32 s60, s60, 73728
	v_mov_b32_e32 v249, s60
	s_lshl_b32 s70, s47, 10
	s_add_u32 s71, s70, 24576
	s_mov_b64 s[74:75], s[48:49]
	s_mov_b64 s[76:77], s[50:51]
	s_mov_b32 s56, 0x4000
	s_mov_b32 s57, 0
	s_mov_b32 s58, 0x2000
	s_add_i32 m0, s57, s70
	s_nop 0
	global_load_lds_dwordx4 v238, s[74:75]
	s_add_u32 s74, s74, 0x10000
	s_addc_u32 s75, s75, 0
	s_lshl_b32 s60, s57, 1
	s_add_i32 s60, s60, s71
	s_mov_b32 m0, s60
	s_nop 0
	global_load_lds_dwordx4 v239, s[76:77]
	s_add_u32 s62, s76, 0x80
	s_addc_u32 s63, s77, 0
	s_add_i32 m0, s60, 0x2000
	s_nop 0
	global_load_lds_dwordx4 v239, s[62:63]
	s_add_u32 s76, s76, 0x10000
	s_addc_u32 s77, s77, 0
	s_add_i32 m0, s58, s70
	s_nop 0
	global_load_lds_dwordx4 v238, s[74:75]
	s_add_u32 s74, s74, 0x10000
	s_addc_u32 s75, s75, 0
	v_lshlrev_b32_e32 v1, 10, v0
	v_lshl_or_b32 v1, v252, 4, v1
	global_load_dwordx4 v[16:19], v1, s[54:55]
	global_load_dwordx4 v[20:23], v1, s[54:55] offset:32
	global_load_dwordx4 v[24:27], v1, s[54:55] offset:64
	global_load_dwordx4 v[28:31], v1, s[54:55] offset:96
	s_add_i32 m0, s56, s70
	s_nop 0
	global_load_lds_dwordx4 v238, s[74:75]
	s_add_u32 s74, s74, 0x10000
	s_addc_u32 s75, s75, 0
	v_mov_b32_e32 v248, 0
	v_mov_b32_e32 v247, 0
	v_mov_b32_e32 v160, 0
	v_mov_b32_e32 v161, 0
	v_mov_b32_e32 v162, 0
	v_mov_b32_e32 v163, 0
	v_mov_b32_e32 v164, 0
	v_mov_b32_e32 v165, 0
	v_mov_b32_e32 v166, 0
	v_mov_b32_e32 v167, 0
	v_mov_b32_e32 v168, 0
	v_mov_b32_e32 v169, 0
	v_mov_b32_e32 v170, 0
	v_mov_b32_e32 v171, 0
	v_mov_b32_e32 v172, 0
	v_mov_b32_e32 v173, 0
	v_mov_b32_e32 v174, 0
	v_mov_b32_e32 v175, 0
	v_mov_b32_e32 v32, 0
	v_mov_b32_e32 v33, 0
	v_mov_b32_e32 v34, 0
	v_mov_b32_e32 v35, 0
	v_mov_b32_e32 v36, 0
	v_mov_b32_e32 v37, 0
	v_mov_b32_e32 v38, 0
	v_mov_b32_e32 v39, 0
	v_mov_b32_e32 v40, 0
	v_mov_b32_e32 v41, 0
	v_mov_b32_e32 v42, 0
	v_mov_b32_e32 v43, 0
	v_mov_b32_e32 v44, 0
	v_mov_b32_e32 v45, 0
	v_mov_b32_e32 v46, 0
	v_mov_b32_e32 v47, 0
	v_mov_b32_e32 v48, 0
	v_mov_b32_e32 v49, 0
	v_mov_b32_e32 v50, 0
	v_mov_b32_e32 v51, 0
	v_mov_b32_e32 v52, 0
	v_mov_b32_e32 v53, 0
	v_mov_b32_e32 v54, 0
	v_mov_b32_e32 v55, 0
	v_mov_b32_e32 v56, 0
	v_mov_b32_e32 v57, 0
	v_mov_b32_e32 v58, 0
	v_mov_b32_e32 v59, 0
	v_mov_b32_e32 v60, 0
	v_mov_b32_e32 v61, 0
	v_mov_b32_e32 v62, 0
	v_mov_b32_e32 v63, 0
	v_mov_b32_e32 v64, 0
	v_mov_b32_e32 v65, 0
	v_mov_b32_e32 v66, 0
	v_mov_b32_e32 v67, 0
	v_mov_b32_e32 v68, 0
	v_mov_b32_e32 v69, 0
	v_mov_b32_e32 v70, 0
	v_mov_b32_e32 v71, 0
	v_mov_b32_e32 v72, 0
	v_mov_b32_e32 v73, 0
	v_mov_b32_e32 v74, 0
	v_mov_b32_e32 v75, 0
	v_mov_b32_e32 v76, 0
	v_mov_b32_e32 v77, 0
	v_mov_b32_e32 v78, 0
	v_mov_b32_e32 v79, 0
	v_mov_b32_e32 v80, 0
	v_mov_b32_e32 v81, 0
	v_mov_b32_e32 v82, 0
	v_mov_b32_e32 v83, 0
	v_mov_b32_e32 v84, 0
	v_mov_b32_e32 v85, 0
	v_mov_b32_e32 v86, 0
	v_mov_b32_e32 v87, 0
	v_mov_b32_e32 v88, 0
	v_mov_b32_e32 v89, 0
	v_mov_b32_e32 v90, 0
	v_mov_b32_e32 v91, 0
	v_mov_b32_e32 v92, 0
	v_mov_b32_e32 v93, 0
	v_mov_b32_e32 v94, 0
	v_mov_b32_e32 v95, 0
	s_mov_b32 s46, 0
	s_waitcnt vmcnt(8) lgkmcnt(0)
	s_barrier
	v_add_u32_e32 v250, s57, v244
	ds_read_b128 v[208:211], v250
	ds_read_b128 v[212:215], v250 offset:512
	ds_read_b128 v[216:219], v250 offset:2048
	ds_read_b128 v[220:223], v250 offset:2560
	ds_read_b128 v[224:227], v250 offset:4096
	ds_read_b128 v[228:231], v250 offset:4608
	ds_read_b128 v[232:235], v250 offset:6144
	ds_read_b128 v[240:243], v250 offset:6656
	s_waitcnt vmcnt(1) lgkmcnt(0)
	v_mfma_f32_32x32x16_bf16 v[96:111], v[208:211], v[16:19], v[160:175]
	v_mfma_f32_32x32x16_bf16 v[112:127], v[212:215], v[16:19], v[160:175]
	v_mfma_f32_32x32x16_bf16 v[96:111], v[216:219], v[20:23], v[96:111]
	v_mfma_f32_32x32x16_bf16 v[112:127], v[220:223], v[20:23], v[112:127]
	v_mfma_f32_32x32x16_bf16 v[96:111], v[224:227], v[24:27], v[96:111]
	v_mfma_f32_32x32x16_bf16 v[112:127], v[228:231], v[24:27], v[112:127]
	v_mfma_f32_32x32x16_bf16 v[96:111], v[232:235], v[28:31], v[96:111]
	v_mfma_f32_32x32x16_bf16 v[112:127], v[240:243], v[28:31], v[112:127]
	s_nop 7
	s_nop 7
	s_cmp_lg_u32 s46, s79
	s_cbranch_scc1 .Lat_nomask_230
	s_sub_u32 s60, s46, s72
	s_lshl_b32 s60, s60, 6
	v_lshl_add_u32 v0, v252, 2, s60
	v_sub_u32_e32 v0, v246, v0
	v_mov_b32_e32 v1, 0xff800000
	v_cmp_gt_i32_e64 s[60:61], 0, v0
	v_cmp_gt_i32_e64 s[62:63], 32, v0
	v_cmp_gt_i32_e64 s[64:65], 1, v0
	v_cmp_gt_i32_e64 s[66:67], 33, v0
	v_cndmask_b32_e64 v96, v96, v1, s[60:61]
	v_cmp_gt_i32_e64 s[60:61], 2, v0
	v_cndmask_b32_e64 v112, v112, v1, s[62:63]
	v_cmp_gt_i32_e64 s[62:63], 34, v0
	v_cndmask_b32_e64 v97, v97, v1, s[64:65]
	v_cmp_gt_i32_e64 s[64:65], 3, v0
	v_cndmask_b32_e64 v113, v113, v1, s[66:67]
	v_cmp_gt_i32_e64 s[66:67], 35, v0
	v_cndmask_b32_e64 v98, v98, v1, s[60:61]
	v_cmp_gt_i32_e64 s[60:61], 8, v0
	v_cndmask_b32_e64 v114, v114, v1, s[62:63]
	v_cmp_gt_i32_e64 s[62:63], 40, v0
	v_cndmask_b32_e64 v99, v99, v1, s[64:65]
	v_cmp_gt_i32_e64 s[64:65], 9, v0
	v_cndmask_b32_e64 v115, v115, v1, s[66:67]
	v_cmp_gt_i32_e64 s[66:67], 41, v0
	v_cndmask_b32_e64 v100, v100, v1, s[60:61]
	v_cmp_gt_i32_e64 s[60:61], 10, v0
	v_cndmask_b32_e64 v116, v116, v1, s[62:63]
	v_cmp_gt_i32_e64 s[62:63], 42, v0
	v_cndmask_b32_e64 v101, v101, v1, s[64:65]
	v_cmp_gt_i32_e64 s[64:65], 11, v0
	v_cndmask_b32_e64 v117, v117, v1, s[66:67]
	v_cmp_gt_i32_e64 s[66:67], 43, v0
	v_cndmask_b32_e64 v102, v102, v1, s[60:61]
	v_cmp_gt_i32_e64 s[60:61], 16, v0
	v_cndmask_b32_e64 v118, v118, v1, s[62:63]
	v_cmp_gt_i32_e64 s[62:63], 48, v0
	v_cndmask_b32_e64 v103, v103, v1, s[64:65]
	v_cmp_gt_i32_e64 s[64:65], 17, v0
	v_cndmask_b32_e64 v119, v119, v1, s[66:67]
	v_cmp_gt_i32_e64 s[66:67], 49, v0
	v_cndmask_b32_e64 v104, v104, v1, s[60:61]
	v_cmp_gt_i32_e64 s[60:61], 18, v0
	v_cndmask_b32_e64 v120, v120, v1, s[62:63]
	v_cmp_gt_i32_e64 s[62:63], 50, v0
	v_cndmask_b32_e64 v105, v105, v1, s[64:65]
	v_cmp_gt_i32_e64 s[64:65], 19, v0
	v_cndmask_b32_e64 v121, v121, v1, s[66:67]
	v_cmp_gt_i32_e64 s[66:67], 51, v0
	v_cndmask_b32_e64 v106, v106, v1, s[60:61]
	v_cmp_gt_i32_e64 s[60:61], 24, v0
	v_cndmask_b32_e64 v122, v122, v1, s[62:63]
	v_cmp_gt_i32_e64 s[62:63], 56, v0
	v_cndmask_b32_e64 v107, v107, v1, s[64:65]
	v_cmp_gt_i32_e64 s[64:65], 25, v0
	v_cndmask_b32_e64 v123, v123, v1, s[66:67]
	v_cmp_gt_i32_e64 s[66:67], 57, v0
	v_cndmask_b32_e64 v108, v108, v1, s[60:61]
	v_cmp_gt_i32_e64 s[60:61], 26, v0
	v_cndmask_b32_e64 v124, v124, v1, s[62:63]
	v_cmp_gt_i32_e64 s[62:63], 58, v0
	v_cndmask_b32_e64 v109, v109, v1, s[64:65]
	v_cmp_gt_i32_e64 s[64:65], 27, v0
	v_cndmask_b32_e64 v125, v125, v1, s[66:67]
	v_cmp_gt_i32_e64 s[66:67], 59, v0
	v_cndmask_b32_e64 v110, v110, v1, s[60:61]
	s_nop 1
	v_cndmask_b32_e64 v126, v126, v1, s[62:63]
	v_cndmask_b32_e64 v111, v111, v1, s[64:65]
	v_cndmask_b32_e64 v127, v127, v1, s[66:67]

.Lat_loop:
	s_cmp_ge_u32 s46, s45
	s_cbranch_scc1 .Lat_drain
	s_cmp_ge_u32 s46, s78
	s_cbranch_scc1 .Lat_lite_443
	s_lshl_b32 s60, s56, 1
	v_add_u32_e32 v250, s60, v245
	v_mfma_f32_32x32x16_bf16 v[128:143], v[208:211], v[16:19], v[160:175]
	v_add_f32_e32 v247, v247, v96
	v_add_f32_e32 v247, v247, v97
	v_add_f32_e32 v247, v247, v98
	v_add_f32_e32 v247, v247, v99
	v_cvt_pk_bf16_f32 v176, v96, v97
	v_cvt_pk_bf16_f32 v177, v98, v99
	v_mfma_f32_32x32x16_bf16 v[144:159], v[212:215], v[16:19], v[160:175]
	v_add_f32_e32 v247, v247, v100
	v_add_f32_e32 v247, v247, v101
	v_add_f32_e32 v247, v247, v102
	v_add_f32_e32 v247, v247, v103
	v_cvt_pk_bf16_f32 v178, v100, v101
	v_cvt_pk_bf16_f32 v179, v102, v103
	v_mfma_f32_32x32x16_bf16 v[128:143], v[216:219], v[20:23], v[128:143]
	v_add_f32_e32 v247, v247, v104
	v_add_f32_e32 v247, v247, v105
	v_add_f32_e32 v247, v247, v106
	v_add_f32_e32 v247, v247, v107
	v_cvt_pk_bf16_f32 v180, v104, v105
	v_cvt_pk_bf16_f32 v181, v106, v107
	v_mfma_f32_32x32x16_bf16 v[144:159], v[220:223], v[20:23], v[144:159]
	v_add_f32_e32 v247, v247, v108
	v_add_f32_e32 v247, v247, v109
	v_add_f32_e32 v247, v247, v110
	v_add_f32_e32 v247, v247, v111
	v_cvt_pk_bf16_f32 v182, v108, v109
	v_cvt_pk_bf16_f32 v183, v110, v111
	v_mfma_f32_32x32x16_bf16 v[128:143], v[224:227], v[24:27], v[128:143]
	v_add_f32_e32 v247, v247, v112
	v_add_f32_e32 v247, v247, v113
	v_add_f32_e32 v247, v247, v114
	v_add_f32_e32 v247, v247, v115
	v_cvt_pk_bf16_f32 v184, v112, v113
	v_cvt_pk_bf16_f32 v185, v114, v115
	v_mfma_f32_32x32x16_bf16 v[144:159], v[228:231], v[24:27], v[144:159]
	v_add_f32_e32 v247, v247, v116
	v_add_f32_e32 v247, v247, v117
	v_add_f32_e32 v247, v247, v118
	v_add_f32_e32 v247, v247, v119
	v_cvt_pk_bf16_f32 v186, v116, v117
	v_cvt_pk_bf16_f32 v187, v118, v119
	v_mfma_f32_32x32x16_bf16 v[128:143], v[232:235], v[28:31], v[128:143]
	v_add_f32_e32 v247, v247, v120
	v_add_f32_e32 v247, v247, v121
	v_add_f32_e32 v247, v247, v122
	v_add_f32_e32 v247, v247, v123
	v_cvt_pk_bf16_f32 v188, v120, v121
	v_cvt_pk_bf16_f32 v189, v122, v123
	ds_read_b64_tr_b16 v[192:193], v250 offset:0
	ds_read_b64_tr_b16 v[194:195], v250 offset:512
	v_mfma_f32_32x32x16_bf16 v[144:159], v[240:243], v[28:31], v[144:159]
	v_add_f32_e32 v247, v247, v124
	v_add_f32_e32 v247, v247, v125
	v_add_f32_e32 v247, v247, v126
	v_add_f32_e32 v247, v247, v127
	v_cvt_pk_bf16_f32 v190, v124, v125
	v_cvt_pk_bf16_f32 v191, v126, v127
	ds_read_b64_tr_b16 v[196:197], v250 offset:4096
	ds_read_b64_tr_b16 v[198:199], v250 offset:4608
	s_add_i32 m0, s57, s70
	s_nop 0
	global_load_lds_dwordx4 v238, s[74:75]
	s_add_u32 s74, s74, 0x10000
	s_addc_u32 s75, s75, 0
	s_lshl_b32 s60, s58, 1
	s_add_i32 s60, s60, s71
	s_mov_b32 m0, s60
	s_nop 0
	global_load_lds_dwordx4 v239, s[76:77]
	s_add_u32 s62, s76, 0x80
	s_addc_u32 s63, s77, 0
	s_add_i32 m0, s60, 0x2000
	s_nop 0
	global_load_lds_dwordx4 v239, s[62:63]
	s_add_u32 s76, s76, 0x10000
	s_addc_u32 s77, s77, 0
	s_cmp_lg_u32 s46, s79
	s_cbranch_scc1 .Lat_nomask_526
	s_sub_u32 s60, s46, s72
	s_lshl_b32 s60, s60, 6
	v_lshl_add_u32 v0, v252, 2, s60
	v_sub_u32_e32 v0, v246, v0
	v_mov_b32_e32 v1, 0xff800000
	v_cmp_gt_i32_e64 s[60:61], 0, v0
	v_cmp_gt_i32_e64 s[62:63], 32, v0
	v_cmp_gt_i32_e64 s[64:65], 1, v0
	v_cmp_gt_i32_e64 s[66:67], 33, v0
	v_cndmask_b32_e64 v128, v128, v1, s[60:61]
	v_cmp_gt_i32_e64 s[60:61], 2, v0
	v_cndmask_b32_e64 v144, v144, v1, s[62:63]
	v_cmp_gt_i32_e64 s[62:63], 34, v0
	v_cndmask_b32_e64 v129, v129, v1, s[64:65]
	v_cmp_gt_i32_e64 s[64:65], 3, v0
	v_cndmask_b32_e64 v145, v145, v1, s[66:67]
	v_cmp_gt_i32_e64 s[66:67], 35, v0
	v_cndmask_b32_e64 v130, v130, v1, s[60:61]
	v_cmp_gt_i32_e64 s[60:61], 8, v0
	v_cndmask_b32_e64 v146, v146, v1, s[62:63]
	v_cmp_gt_i32_e64 s[62:63], 40, v0
	v_cndmask_b32_e64 v131, v131, v1, s[64:65]
	v_cmp_gt_i32_e64 s[64:65], 9, v0
	v_cndmask_b32_e64 v147, v147, v1, s[66:67]
	v_cmp_gt_i32_e64 s[66:67], 41, v0
	v_cndmask_b32_e64 v132, v132, v1, s[60:61]
	v_cmp_gt_i32_e64 s[60:61], 10, v0
	v_cndmask_b32_e64 v148, v148, v1, s[62:63]
	v_cmp_gt_i32_e64 s[62:63], 42, v0
	v_cndmask_b32_e64 v133, v133, v1, s[64:65]
	v_cmp_gt_i32_e64 s[64:65], 11, v0
	v_cndmask_b32_e64 v149, v149, v1, s[66:67]
	v_cmp_gt_i32_e64 s[66:67], 43, v0
	v_cndmask_b32_e64 v134, v134, v1, s[60:61]
	v_cmp_gt_i32_e64 s[60:61], 16, v0
	v_cndmask_b32_e64 v150, v150, v1, s[62:63]
	v_cmp_gt_i32_e64 s[62:63], 48, v0
	v_cndmask_b32_e64 v135, v135, v1, s[64:65]
	v_cmp_gt_i32_e64 s[64:65], 17, v0
	v_cndmask_b32_e64 v151, v151, v1, s[66:67]
	v_cmp_gt_i32_e64 s[66:67], 49, v0
	v_cndmask_b32_e64 v136, v136, v1, s[60:61]
	v_cmp_gt_i32_e64 s[60:61], 18, v0
	v_cndmask_b32_e64 v152, v152, v1, s[62:63]
	v_cmp_gt_i32_e64 s[62:63], 50, v0
	v_cndmask_b32_e64 v137, v137, v1, s[64:65]
	v_cmp_gt_i32_e64 s[64:65], 19, v0
	v_cndmask_b32_e64 v153, v153, v1, s[66:67]
	v_cmp_gt_i32_e64 s[66:67], 51, v0
	v_cndmask_b32_e64 v138, v138, v1, s[60:61]
	v_cmp_gt_i32_e64 s[60:61], 24, v0
	v_cndmask_b32_e64 v154, v154, v1, s[62:63]
	v_cmp_gt_i32_e64 s[62:63], 56, v0
	v_cndmask_b32_e64 v139, v139, v1, s[64:65]
	v_cmp_gt_i32_e64 s[64:65], 25, v0
	v_cndmask_b32_e64 v155, v155, v1, s[66:67]
	v_cmp_gt_i32_e64 s[66:67], 57, v0
	v_cndmask_b32_e64 v140, v140, v1, s[60:61]
	v_cmp_gt_i32_e64 s[60:61], 26, v0
	v_cndmask_b32_e64 v156, v156, v1, s[62:63]
	v_cmp_gt_i32_e64 s[62:63], 58, v0
	v_cndmask_b32_e64 v141, v141, v1, s[64:65]
	v_cmp_gt_i32_e64 s[64:65], 27, v0
	v_cndmask_b32_e64 v157, v157, v1, s[66:67]
	v_cmp_gt_i32_e64 s[66:67], 59, v0
	v_cndmask_b32_e64 v142, v142, v1, s[60:61]
	s_nop 1
	v_cndmask_b32_e64 v158, v158, v1, s[62:63]
	v_cndmask_b32_e64 v143, v143, v1, s[64:65]
	v_cndmask_b32_e64 v159, v159, v1, s[66:67]

.Lat_norescO_443:
.Lat_next_443:
	s_cmp_ge_u32 s46, s45
	s_cbranch_scc1 .Lat_drain
	s_cmp_ge_u32 s46, s78
	s_cbranch_scc1 .Lat_lite_862
	s_lshl_b32 s60, s56, 1
	v_add_u32_e32 v250, s60, v245
	v_mfma_f32_32x32x16_bf16 v[96:111], v[208:211], v[16:19], v[160:175]
	v_add_f32_e32 v247, v247, v128
	v_add_f32_e32 v247, v247, v129
	v_add_f32_e32 v247, v247, v130
	v_add_f32_e32 v247, v247, v131
	v_cvt_pk_bf16_f32 v176, v128, v129
	v_cvt_pk_bf16_f32 v177, v130, v131
	v_mfma_f32_32x32x16_bf16 v[112:127], v[212:215], v[16:19], v[160:175]
	v_add_f32_e32 v247, v247, v132
	v_add_f32_e32 v247, v247, v133
	v_add_f32_e32 v247, v247, v134
	v_add_f32_e32 v247, v247, v135
	v_cvt_pk_bf16_f32 v178, v132, v133
	v_cvt_pk_bf16_f32 v179, v134, v135
	v_mfma_f32_32x32x16_bf16 v[96:111], v[216:219], v[20:23], v[96:111]
	v_add_f32_e32 v247, v247, v136
	v_add_f32_e32 v247, v247, v137
	v_add_f32_e32 v247, v247, v138
	v_add_f32_e32 v247, v247, v139
	v_cvt_pk_bf16_f32 v180, v136, v137
	v_cvt_pk_bf16_f32 v181, v138, v139
	v_mfma_f32_32x32x16_bf16 v[112:127], v[220:223], v[20:23], v[112:127]
	v_add_f32_e32 v247, v247, v140
	v_add_f32_e32 v247, v247, v141
	v_add_f32_e32 v247, v247, v142
	v_add_f32_e32 v247, v247, v143
	v_cvt_pk_bf16_f32 v182, v140, v141
	v_cvt_pk_bf16_f32 v183, v142, v143
	v_mfma_f32_32x32x16_bf16 v[96:111], v[224:227], v[24:27], v[96:111]
	v_add_f32_e32 v247, v247, v144
	v_add_f32_e32 v247, v247, v145
	v_add_f32_e32 v247, v247, v146
	v_add_f32_e32 v247, v247, v147
	v_cvt_pk_bf16_f32 v184, v144, v145
	v_cvt_pk_bf16_f32 v185, v146, v147
	v_mfma_f32_32x32x16_bf16 v[112:127], v[228:231], v[24:27], v[112:127]
	v_add_f32_e32 v247, v247, v148
	v_add_f32_e32 v247, v247, v149
	v_add_f32_e32 v247, v247, v150
	v_add_f32_e32 v247, v247, v151
	v_cvt_pk_bf16_f32 v186, v148, v149
	v_cvt_pk_bf16_f32 v187, v150, v151
	v_mfma_f32_32x32x16_bf16 v[96:111], v[232:235], v[28:31], v[96:111]
	v_add_f32_e32 v247, v247, v152
	v_add_f32_e32 v247, v247, v153
	v_add_f32_e32 v247, v247, v154
	v_add_f32_e32 v247, v247, v155
	v_cvt_pk_bf16_f32 v188, v152, v153
	v_cvt_pk_bf16_f32 v189, v154, v155
	ds_read_b64_tr_b16 v[192:193], v250 offset:0
	ds_read_b64_tr_b16 v[194:195], v250 offset:512
	v_mfma_f32_32x32x16_bf16 v[112:127], v[240:243], v[28:31], v[112:127]
	v_add_f32_e32 v247, v247, v156
	v_add_f32_e32 v247, v247, v157
	v_add_f32_e32 v247, v247, v158
	v_add_f32_e32 v247, v247, v159
	v_cvt_pk_bf16_f32 v190, v156, v157
	v_cvt_pk_bf16_f32 v191, v158, v159
	ds_read_b64_tr_b16 v[196:197], v250 offset:4096
	ds_read_b64_tr_b16 v[198:199], v250 offset:4608
	s_add_i32 m0, s57, s70
	s_nop 0
	global_load_lds_dwordx4 v238, s[74:75]
	s_add_u32 s74, s74, 0x10000
	s_addc_u32 s75, s75, 0
	s_lshl_b32 s60, s58, 1
	s_add_i32 s60, s60, s71
	s_mov_b32 m0, s60
	s_nop 0
	global_load_lds_dwordx4 v239, s[76:77]
	s_add_u32 s62, s76, 0x80
	s_addc_u32 s63, s77, 0
	s_add_i32 m0, s60, 0x2000
	s_nop 0
	global_load_lds_dwordx4 v239, s[62:63]
	s_add_u32 s76, s76, 0x10000
	s_addc_u32 s77, s77, 0
	s_cmp_lg_u32 s46, s79
	s_cbranch_scc1 .Lat_nomask_945
	s_sub_u32 s60, s46, s72
	s_lshl_b32 s60, s60, 6
	v_lshl_add_u32 v0, v252, 2, s60
	v_sub_u32_e32 v0, v246, v0
	v_mov_b32_e32 v1, 0xff800000
	v_cmp_gt_i32_e64 s[60:61], 0, v0
	v_cmp_gt_i32_e64 s[62:63], 32, v0
	v_cmp_gt_i32_e64 s[64:65], 1, v0
	v_cmp_gt_i32_e64 s[66:67], 33, v0
	v_cndmask_b32_e64 v96, v96, v1, s[60:61]
	v_cmp_gt_i32_e64 s[60:61], 2, v0
	v_cndmask_b32_e64 v112, v112, v1, s[62:63]
	v_cmp_gt_i32_e64 s[62:63], 34, v0
	v_cndmask_b32_e64 v97, v97, v1, s[64:65]
	v_cmp_gt_i32_e64 s[64:65], 3, v0
	v_cndmask_b32_e64 v113, v113, v1, s[66:67]
	v_cmp_gt_i32_e64 s[66:67], 35, v0
	v_cndmask_b32_e64 v98, v98, v1, s[60:61]
	v_cmp_gt_i32_e64 s[60:61], 8, v0
	v_cndmask_b32_e64 v114, v114, v1, s[62:63]
	v_cmp_gt_i32_e64 s[62:63], 40, v0
	v_cndmask_b32_e64 v99, v99, v1, s[64:65]
	v_cmp_gt_i32_e64 s[64:65], 9, v0
	v_cndmask_b32_e64 v115, v115, v1, s[66:67]
	v_cmp_gt_i32_e64 s[66:67], 41, v0
	v_cndmask_b32_e64 v100, v100, v1, s[60:61]
	v_cmp_gt_i32_e64 s[60:61], 10, v0
	v_cndmask_b32_e64 v116, v116, v1, s[62:63]
	v_cmp_gt_i32_e64 s[62:63], 42, v0
	v_cndmask_b32_e64 v101, v101, v1, s[64:65]
	v_cmp_gt_i32_e64 s[64:65], 11, v0
	v_cndmask_b32_e64 v117, v117, v1, s[66:67]
	v_cmp_gt_i32_e64 s[66:67], 43, v0
	v_cndmask_b32_e64 v102, v102, v1, s[60:61]
	v_cmp_gt_i32_e64 s[60:61], 16, v0
	v_cndmask_b32_e64 v118, v118, v1, s[62:63]
	v_cmp_gt_i32_e64 s[62:63], 48, v0
	v_cndmask_b32_e64 v103, v103, v1, s[64:65]
	v_cmp_gt_i32_e64 s[64:65], 17, v0
	v_cndmask_b32_e64 v119, v119, v1, s[66:67]
	v_cmp_gt_i32_e64 s[66:67], 49, v0
	v_cndmask_b32_e64 v104, v104, v1, s[60:61]
	v_cmp_gt_i32_e64 s[60:61], 18, v0
	v_cndmask_b32_e64 v120, v120, v1, s[62:63]
	v_cmp_gt_i32_e64 s[62:63], 50, v0
	v_cndmask_b32_e64 v105, v105, v1, s[64:65]
	v_cmp_gt_i32_e64 s[64:65], 19, v0
	v_cndmask_b32_e64 v121, v121, v1, s[66:67]
	v_cmp_gt_i32_e64 s[66:67], 51, v0
	v_cndmask_b32_e64 v106, v106, v1, s[60:61]
	v_cmp_gt_i32_e64 s[60:61], 24, v0
	v_cndmask_b32_e64 v122, v122, v1, s[62:63]
	v_cmp_gt_i32_e64 s[62:63], 56, v0
	v_cndmask_b32_e64 v107, v107, v1, s[64:65]
	v_cmp_gt_i32_e64 s[64:65], 25, v0
	v_cndmask_b32_e64 v123, v123, v1, s[66:67]
	v_cmp_gt_i32_e64 s[66:67], 57, v0
	v_cndmask_b32_e64 v108, v108, v1, s[60:61]
	v_cmp_gt_i32_e64 s[60:61], 26, v0
	v_cndmask_b32_e64 v124, v124, v1, s[62:63]
	v_cmp_gt_i32_e64 s[62:63], 58, v0
	v_cndmask_b32_e64 v109, v109, v1, s[64:65]
	v_cmp_gt_i32_e64 s[64:65], 27, v0
	v_cndmask_b32_e64 v125, v125, v1, s[66:67]
	v_cmp_gt_i32_e64 s[66:67], 59, v0
	v_cndmask_b32_e64 v110, v110, v1, s[60:61]
	s_nop 1
	v_cndmask_b32_e64 v126, v126, v1, s[62:63]
	v_cndmask_b32_e64 v111, v111, v1, s[64:65]
	v_cndmask_b32_e64 v127, v127, v1, s[66:67]
